# stack + six broadcast v_mov copies in scan step 1 replaced by op_sel high-half operands
# speedup vs baseline: 1.0059x; 1.0009x over previous
.LBB0_554:
	s_or_b64 exec, exec, s[18:19]
	s_waitcnt lgkmcnt(2)
	v_pk_add_f32 v[82:83], v[132:133], v[82:83] op_sel:[1,0] op_sel_hi:[1,1]
	v_exp_f32_e32 v82, v82
	v_exp_f32_e32 v83, v83
	v_pk_add_f32 v[84:85], v[132:133], v[84:85] op_sel:[1,0] op_sel_hi:[1,1]
	v_exp_f32_e32 v84, v84
	v_exp_f32_e32 v85, v85
	v_pk_add_f32 v[82:83], v[82:83], 1.0 op_sel_hi:[1,0]
	v_rcp_f32_e32 v82, v82
	v_rcp_f32_e32 v83, v83
	v_pk_add_f32 v[84:85], v[84:85], 1.0 op_sel_hi:[1,0]
	v_rcp_f32_e32 v84, v84
	v_rcp_f32_e32 v85, v85
	v_pk_mul_f32 v[122:123], v[82:83], s[70:71] op_sel_hi:[1,0]
	v_pk_fma_f32 v[124:125], v[82:83], s[70:71], v[122:123] op_sel:[0,0,1] op_sel_hi:[1,0,0]
	v_mul_f32_e32 v2, 0xbf60028a, v85
	v_pk_fma_f32 v[126:127], v[84:85], s[70:71], v[124:125] op_sel_hi:[1,0,1]
	v_mov_b32_e32 v123, v124
	v_pk_add_f32 v[128:129], v[2:3], v[126:127] op_sel_hi:[0,1]
	v_mov_b32_e32 v82, v128
	v_mov_b32_e32 v84, v128
	s_nop 1
	v_permlane16_swap_b32_e32 v82, v84
	v_mov_b32_e32 v83, v82
	v_mov_b32_e32 v85, v84
	s_nop 1
	v_permlane32_swap_b32_e32 v82, v83
	v_permlane32_swap_b32_e32 v84, v85
	v_mov_b32_e32 v127, v128
	v_mov_b32_e32 v104, v105
	v_cndmask_b32_e64 v4, v82, 0, s[10:11]
	v_cndmask_b32_e64 v86, 0, v84, s[12:13]
	v_add_f32_e32 v4, v4, v86
	v_cndmask_b32_e64 v86, 0, v83, s[14:15]
	v_add_f32_e32 v4, v4, v86
	v_pk_add_f32 v[124:125], v[122:123], v[4:5] op_sel_hi:[1,0]
	v_pk_add_f32 v[126:127], v[126:127], v[4:5] op_sel_hi:[1,0]
	v_sub_f32_e32 v4, v124, v122
	v_exp_f32_e32 v122, v4
	v_pk_add_f32 v[80:81], v[116:117], v[80:81] op_sel:[1,0] op_sel_hi:[1,1]
	v_pk_add_f32 v[78:79], v[116:117], v[78:79] op_sel:[1,0] op_sel_hi:[1,1]
	v_exp_f32_e32 v80, v80
	v_exp_f32_e32 v81, v81
	v_exp_f32_e32 v78, v78
	v_exp_f32_e32 v79, v79
	v_mov_b32_e32 v105, v112
	v_mov_b32_e32 v118, v113
	v_mov_b32_e32 v119, v114
	v_pk_add_f32 v[80:81], v[80:81], 1.0 op_sel_hi:[1,0]
	v_mov_b32_e32 v4, v91
	v_pk_mul_f32 v[90:91], v[112:113], v[94:95] op_sel:[0,1] op_sel_hi:[1,1]
	v_mov_b32_e32 v88, v93
	v_pk_mul_f32 v[92:93], v[114:115], v[94:95] op_sel:[0,1] op_sel_hi:[1,1]
	v_mov_b32_e32 v106, v107
	v_mov_b32_e32 v107, v108
	v_mov_b32_e32 v98, v115
	v_pk_add_f32 v[78:79], v[78:79], 1.0 op_sel_hi:[1,0]
	v_rcp_f32_e32 v80, v80
	v_rcp_f32_e32 v81, v81
	v_pk_fma_f32 v[90:91], v[104:105], v[4:5], v[90:91] op_sel_hi:[1,0,1]
	v_pk_fma_f32 v[92:93], v[118:119], v[4:5], v[92:93] op_sel_hi:[1,0,1]
	v_mov_b32_e32 v4, v87
	v_pk_mul_f32 v[94:95], v[108:109], v[102:103] op_sel:[0,1] op_sel_hi:[1,1]
	v_mov_b32_e32 v120, v109
	v_mov_b32_e32 v121, v110
	v_exp_f32_e32 v128, v124
	v_rcp_f32_e32 v78, v78
	v_rcp_f32_e32 v79, v79
	v_pk_fma_f32 v[90:91], v[118:119], v[88:89], v[90:91] op_sel_hi:[1,0,1]
	v_pk_fma_f32 v[92:93], v[98:99], v[88:89], v[92:93] op_sel_hi:[1,0,1]
	v_pk_fma_f32 v[94:95], v[106:107], v[4:5], v[94:95] op_sel_hi:[1,0,1]
	v_pk_mul_f32 v[86:87], v[110:111], v[102:103] op_sel:[0,1] op_sel_hi:[1,1]
	v_mov_b32_e32 v2, v111
	v_pk_fma_f32 v[94:95], v[120:121], v[100:101], v[94:95] op_sel:[0,1,0] op_sel_hi:[1,1,1]
	v_pk_fma_f32 v[86:87], v[120:121], v[4:5], v[86:87] op_sel_hi:[1,0,1]
	v_exp_f32_e32 v129, v125
	v_exp_f32_e32 v130, v126
	v_exp_f32_e64 v132, -v124
	v_exp_f32_e64 v133, -v125
	v_pk_fma_f32 v[2:3], v[2:3], v[100:101], v[86:87] op_sel:[0,1,0] op_sel_hi:[1,1,1]
	v_pk_mul_f32 v[86:87], v[96:97], v[94:95] op_sel:[1,0] op_sel_hi:[1,1]
	v_pk_mul_f32 v[74:75], v[74:75], v[86:87]
	v_pk_mul_f32 v[86:87], v[96:97], v[2:3] op_sel:[1,0] op_sel_hi:[1,1]
	v_mov_b32_e32 v4, v89
	v_pk_add_f32 v[88:89], v[80:81], -1.0 op_sel_hi:[1,0]
	v_exp_f32_e32 v131, v127
	v_exp_f32_e64 v126, -v126
	v_exp_f32_e64 v127, -v127
	v_mov_b32_e32 v123, v128
	v_pk_mul_f32 v[76:77], v[76:77], v[86:87]
	v_pk_add_f32 v[86:87], v[78:79], -1.0 op_sel_hi:[1,0]
	v_pk_mul_f32 v[88:89], v[4:5], v[88:89] op_sel_hi:[0,1]
	v_pk_mul_f32 v[86:87], v[4:5], v[86:87] op_sel_hi:[0,1]
	v_pk_fma_f32 v[2:3], v[2:3], v[88:89], v[2:3]
	v_pk_mul_f32 v[88:89], v[74:75], v[122:123] neg_lo:[0,1] neg_hi:[0,1]
	v_pk_mul_f32 v[74:75], v[74:75], v[78:79]
	v_mov_b32_e32 v124, v129
	v_mov_b32_e32 v125, v130
	v_pk_fma_f32 v[86:87], v[94:95], v[86:87], v[94:95]
	v_pk_mul_f32 v[74:75], v[74:75], v[132:133]
	v_pk_mul_f32 v[94:95], v[76:77], v[124:125] neg_lo:[0,1] neg_hi:[0,1]
	v_pk_mul_f32 v[76:77], v[76:77], v[80:81]
	v_pk_mul_f32 v[78:79], v[86:87], v[132:133]
	v_pk_mul_f32 v[80:81], v[90:91], v[128:129]
	v_pk_mul_f32 v[76:77], v[76:77], v[126:127]
	v_pk_mul_f32 v[2:3], v[2:3], v[126:127]
	v_pk_mul_f32 v[86:87], v[92:93], v[130:131]
	v_cvt_pk_bf16_f32 v74, v74, v75
	v_cvt_pk_bf16_f32 v75, v76, v77
	v_cvt_pk_bf16_f32 v76, v78, v79
	v_cvt_pk_bf16_f32 v77, v2, v3
	v_cvt_pk_bf16_f32 v78, v88, v89
	v_cvt_pk_bf16_f32 v79, v94, v95
	v_cvt_pk_bf16_f32 v80, v80, v81
	v_cvt_pk_bf16_f32 v81, v86, v87
	ds_write_b128 v194, v[74:77] offset:32768
	ds_write_b128 v194, v[78:81]
	s_and_saveexec_b64 s[18:19], s[10:11]
	s_cbranch_execz .LBB0_556
	s_waitcnt lgkmcnt(2)
	v_pk_add_f32 v[2:3], v[84:85], v[82:83]
	s_nop 0
	v_add_f32_e32 v2, v2, v3
	v_exp_f32_e32 v2, v2
	ds_write_b32 v171, v2 offset:21056
